# attention loop top reordered: 8 K ds_reads issued before the (saddr-form) LDS-DMA block so LDS latency overlaps DMA issue; plus no-setprio + pipelined mem-attention reads
# speedup vs baseline: 1.0012x; 1.0012x over previous
; __device__ __forceinline__ float qkt_deep(f32x16& p0, f32x16& p1, const int (&ka)[4], const bf16x8 (&qr)[8]) {
;   bf16x8 kb[8]; float pm;
;   asm volatile("s_waitcnt lgkmcnt(0)" ::: "memory"); SBAR();
;   QD_RD0(0); QD_RD0(1); QD_RD0(2); QD_RD0(3); QD_RD0(4); QD_RD0(5); QD_RD0(6); QD_RD0(7);
;   QK_WAIT(7); QD_MM0(0); SBAR(); QD_RD1(0);
;   QK_WAIT(7); QD_MM0(1); SBAR(); QD_RD1(1);
;   QK_WAIT(7); QD_MM0(2); SBAR(); QD_RD1(2);
;   QK_WAIT(7); QD_MM0(3); SBAR(); QD_RD1(3);
;   QK_WAIT(7); QD_MM0(4); SBAR(); QD_RD1(4);
;   QK_WAIT(7); QD_MM0(5); SBAR(); QD_RD1(5);
;   QK_WAIT(7); QD_MM0(6); SBAR(); QD_RD1(6);
;   QK_WAIT(7); QD_MM0(7); SBAR(); QD_RD1(7);
;   QK_WAIT(7); QD_MM1(0); pm = fmaxf(p0[0], p0[1]); SBAR();
;   QK_WAIT(6); QD_MM1(1); pm = fmaxf(fmaxf(pm, p0[2]), p0[3]); SBAR();
;   QK_WAIT(5); QD_MM1(2); pm = fmaxf(fmaxf(pm, p0[4]), p0[5]); SBAR();
;   QK_WAIT(4); QD_MM1(3); pm = fmaxf(fmaxf(pm, p0[6]), p0[7]); SBAR();
;   QK_WAIT(3); QD_MM1(4); pm = fmaxf(fmaxf(pm, p0[8]), p0[9]); SBAR();
;   QK_WAIT(2); QD_MM1(5); pm = fmaxf(fmaxf(pm, p0[10]), p0[11]); SBAR();
;   QK_WAIT(1); QD_MM1(6); pm = fmaxf(fmaxf(pm, p0[12]), p0[13]); SBAR();
; template <int LD>
; __device__ __forceinline__ void attn256_body(const bf16_t* __restrict__ Qb, const bf16_t* __restrict__ Kh, const unsigned char* __restrict__ Vimg, int seq, char* lds, LAS unsigned char* ldsl,
;                                              f32x16 (&o)[8], float (&rli)[16]) {
;     ...
;   for (int j = 0; j < NT; ++j) {
;     const int cur = j & 1;
;     if (j + 1 < NT) { if (cur) A2_DMA(0, (j + 1) * 64); else A2_DMA(1, (j + 1) * 64); }
;     f32x16 p0 = f32x16{}, p1 = f32x16{}; float pmax;
;     { int ka[4];
; #pragma unroll
;       for (int q = 0; q < 4; ++q) ka[q] = kbase + cur * A2_STAGE + (((2 * q + hi) ^ (r32 & 7)) << 4);
;       pmax = qkt_deep(p0, p1, ka, qr); }
; #pragma unroll
;     for (int r = 0; r < 16; ++r) pmax = fmaxf(pmax, p1[r]);
;     pmax = half_swap_max(pmax);
;     float mn, alpha;
;     if (__builtin_expect(__all(pmax - m_reg <= ATT_THR / ATT_SCALE), 1)) { mn = m_reg; alpha = 1.f; }
;     else { mn = fmaxf(m_reg, pmax); alpha = __builtin_amdgcn_exp2f((m_reg - mn) * C); m_reg = mn; }
;     const float mnC = -mn * C; float ps;
;     if (__any(alpha < 1.f)) { if (hi == 0) al_l[r32] = alpha; asm volatile("s_waitcnt lgkmcnt(0)" ::: "memory");
.LBB0_662:
.LBB0_663:
	s_mul_i32 s4, s4, 0xc000
	s_waitcnt lgkmcnt(0)
	v_add_u32_e32 v0, s4, v221
	v_add_u32_e32 v14, v0, v233
	v_add_u32_e32 v15, v0, v234
	v_add_u32_e32 v252, v0, v235
	v_add_u32_e32 v0, v0, v236
	ds_read_b128 v[2:5], v14 offset:0
	ds_read_b128 v[6:9], v15 offset:0
	ds_read_b128 v[10:13], v252 offset:0
	ds_read_b128 v[144:147], v0 offset:0
	ds_read_b128 v[148:151], v14 offset:0x80
	ds_read_b128 v[152:155], v15 offset:0x80
	ds_read_b128 v[156:159], v252 offset:0x80
	ds_read_b128 v[208:211], v0 offset:0x80
	s_cmpk_eq_i32 s45, 0xff
	s_cbranch_scc1 .Lnodma_a
	s_cmp_eq_u32 s4, 0
	s_cselect_b32 m0, s56, s0
	s_cselect_b32 s5, s89, 0x2000
	s_cselect_b32 s6, s57, s1
	s_cselect_b32 s7, s60, s28
	s_cselect_b32 s8, s61, s29
	s_cselect_b32 s9, s62, s52
	global_load_lds_dwordx4 v226, s[98:99]
	s_add_i32 m0, s0, s5
	s_nop 0
	global_load_lds_dwordx4 v224, s[98:99]
	s_mov_b32 m0, s6
	s_add_u32 s98, s98, 0x100000
	s_addc_u32 s99, s99, 0
	global_load_lds_dwordx4 v222, s[100:101]
	s_mov_b32 m0, s7
	s_add_u32 s100, s100, 0x2000
	s_addc_u32 s101, s101, 0
	global_load_lds_dwordx4 v222, s[100:101]
	s_mov_b32 m0, s8
	s_add_u32 s100, s100, 0x2000
	s_addc_u32 s101, s101, 0
	global_load_lds_dwordx4 v222, s[100:101]
	s_mov_b32 m0, s9
	s_add_u32 s100, s100, 0x2000
	s_addc_u32 s101, s101, 0
	global_load_lds_dwordx4 v222, s[100:101]
	s_add_u32 s100, s100, 0x2000
	s_addc_u32 s101, s101, 0
.Lnodma_a:
	s_waitcnt lgkmcnt(7)
	s_nop 0
	v_mfma_f32_32x32x16_bf16 v[160:175], v[2:5], v[176:179], 0
	ds_read_b128 v[2:5], v14 offset:0x2000
	s_waitcnt lgkmcnt(7)
	s_nop 0
	v_mfma_f32_32x32x16_bf16 v[160:175], v[6:9], v[180:183], v[160:175]
	ds_read_b128 v[6:9], v15 offset:0x2000
	s_waitcnt lgkmcnt(7)
	s_nop 0
	v_mfma_f32_32x32x16_bf16 v[160:175], v[10:13], v[184:187], v[160:175]
	ds_read_b128 v[10:13], v252 offset:0x2000
	s_waitcnt lgkmcnt(7)
	s_nop 0
	v_mfma_f32_32x32x16_bf16 v[160:175], v[144:147], v[188:191], v[160:175]
	ds_read_b128 v[240:243], v0 offset:0x2000
	s_waitcnt lgkmcnt(7)
	s_nop 0
	v_mfma_f32_32x32x16_bf16 v[160:175], v[148:151], v[192:195], v[160:175]
	ds_read_b128 v[244:247], v14 offset:0x2080
	s_waitcnt lgkmcnt(7)
	s_nop 0
	v_mfma_f32_32x32x16_bf16 v[160:175], v[152:155], v[196:199], v[160:175]
	ds_read_b128 v[248:251], v15 offset:0x2080
	s_waitcnt lgkmcnt(7)
	s_nop 0
	v_mfma_f32_32x32x16_bf16 v[160:175], v[156:159], v[200:203], v[160:175]
	ds_read_b128 v[212:215], v252 offset:0x2080
	s_waitcnt lgkmcnt(7)
	s_nop 0
	v_mfma_f32_32x32x16_bf16 v[160:175], v[208:211], v[204:207], v[160:175]
	ds_read_b128 v[208:211], v0 offset:0x2080
	s_waitcnt lgkmcnt(7)
	v_mfma_f32_32x32x16_bf16 v[144:159], v[2:5], v[176:179], 0
	s_nop 10
	v_max_f32_e32 v0, v161, v161
	v_max_f32_e32 v2, v160, v160
	v_max_f32_e32 v0, v2, v0
	s_waitcnt lgkmcnt(6)
	s_nop 0
	v_mfma_f32_32x32x16_bf16 v[144:159], v[6:9], v[180:183], v[144:159]
	v_max3_f32 v0, v0, v162, v163
	s_waitcnt lgkmcnt(5)
	s_nop 0
	v_mfma_f32_32x32x16_bf16 v[144:159], v[10:13], v[184:187], v[144:159]
	v_max3_f32 v0, v0, v164, v165
	s_waitcnt lgkmcnt(4)
	s_nop 0
	v_mfma_f32_32x32x16_bf16 v[144:159], v[240:243], v[188:191], v[144:159]
	v_max3_f32 v0, v0, v166, v167
	s_waitcnt lgkmcnt(3)
	s_nop 0
	v_mfma_f32_32x32x16_bf16 v[144:159], v[244:247], v[192:195], v[144:159]
	v_max3_f32 v0, v0, v168, v169
	s_waitcnt lgkmcnt(2)
	s_nop 0
	v_mfma_f32_32x32x16_bf16 v[144:159], v[248:251], v[196:199], v[144:159]
	v_max3_f32 v0, v0, v170, v171
	s_waitcnt lgkmcnt(1)
	s_nop 0
	v_mfma_f32_32x32x16_bf16 v[144:159], v[212:215], v[200:203], v[144:159]
	v_max3_f32 v0, v0, v172, v173
	s_waitcnt lgkmcnt(0)
	s_nop 0
	v_mfma_f32_32x32x16_bf16 v[144:159], v[208:211], v[204:207], v[144:159]
	v_max3_f32 v0, v0, v174, v175
	s_nop 10
	v_max3_f32 v0, v0, v144, v145
	v_max3_f32 v0, v0, v146, v147
	v_max3_f32 v0, v0, v148, v149
	v_max3_f32 v0, v0, v150, v151
	v_max3_f32 v0, v0, v152, v153
	v_max3_f32 v0, v0, v154, v155
	v_max3_f32 v0, v0, v156, v157
	v_max3_f32 v0, v0, v158, v159
	v_mov_b32_e32 v2, v0
	s_nop 1
	v_permlane32_swap_b32_e32 v0, v2
	v_max_f32_e32 v2, v2, v2
	v_max_f32_e32 v0, v0, v0
	v_max_f32_e32 v2, v0, v2
	v_sub_f32_e32 v0, v2, v238
	v_cmp_ge_f32_e32 vcc, s93, v0
	s_cmp_eq_u64 vcc, exec
	v_mov_b32_e32 v0, 1.0
	s_cbranch_scc0 .LBB0_670
	v_cmp_gt_f32_e32 vcc, 1.0, v0
	s_cbranch_vccz .LBB0_668

; __device__ __forceinline__ float qkt_deep(f32x16& p0, f32x16& p1, const int (&ka)[4], const bf16x8 (&qr)[8]) {
;   bf16x8 kb[8]; float pm;
;   asm volatile("s_waitcnt lgkmcnt(0)" ::: "memory"); SBAR();
;   QD_RD0(0); QD_RD0(1); QD_RD0(2); QD_RD0(3); QD_RD0(4); QD_RD0(5); QD_RD0(6); QD_RD0(7);
;   QK_WAIT(7); QD_MM0(0); SBAR(); QD_RD1(0);
;   QK_WAIT(7); QD_MM0(1); SBAR(); QD_RD1(1);
;   QK_WAIT(7); QD_MM0(2); SBAR(); QD_RD1(2);
;   QK_WAIT(7); QD_MM0(3); SBAR(); QD_RD1(3);
;   QK_WAIT(7); QD_MM0(4); SBAR(); QD_RD1(4);
;   QK_WAIT(7); QD_MM0(5); SBAR(); QD_RD1(5);
;   QK_WAIT(7); QD_MM0(6); SBAR(); QD_RD1(6);
;   QK_WAIT(7); QD_MM0(7); SBAR(); QD_RD1(7);
;   QK_WAIT(7); QD_MM1(0); pm = fmaxf(p0[0], p0[1]); SBAR();
;   QK_WAIT(6); QD_MM1(1); pm = fmaxf(fmaxf(pm, p0[2]), p0[3]); SBAR();
;   QK_WAIT(5); QD_MM1(2); pm = fmaxf(fmaxf(pm, p0[4]), p0[5]); SBAR();
;   QK_WAIT(4); QD_MM1(3); pm = fmaxf(fmaxf(pm, p0[6]), p0[7]); SBAR();
;   QK_WAIT(3); QD_MM1(4); pm = fmaxf(fmaxf(pm, p0[8]), p0[9]); SBAR();
;   QK_WAIT(2); QD_MM1(5); pm = fmaxf(fmaxf(pm, p0[10]), p0[11]); SBAR();
;   QK_WAIT(1); QD_MM1(6); pm = fmaxf(fmaxf(pm, p0[12]), p0[13]); SBAR();
; template <int LD>
; __device__ __forceinline__ void attn256_body(const bf16_t* __restrict__ Qb, const bf16_t* __restrict__ Kh, const unsigned char* __restrict__ Vimg, int seq, char* lds, LAS unsigned char* ldsl,
;                                              f32x16 (&o)[8], float (&rli)[16]) {
;     ...
;   for (int j = 0; j < NT; ++j) {
;     const int cur = j & 1;
;     if (j + 1 < NT) { if (cur) A2_DMA(0, (j + 1) * 64); else A2_DMA(1, (j + 1) * 64); }
;     f32x16 p0 = f32x16{}, p1 = f32x16{}; float pmax;
;     { int ka[4];
; #pragma unroll
;       for (int q = 0; q < 4; ++q) ka[q] = kbase + cur * A2_STAGE + (((2 * q + hi) ^ (r32 & 7)) << 4);
;       pmax = qkt_deep(p0, p1, ka, qr); }
; #pragma unroll
;     for (int r = 0; r < 16; ++r) pmax = fmaxf(pmax, p1[r]);
;     pmax = half_swap_max(pmax);
;     float mn, alpha;
;     if (__builtin_expect(__all(pmax - m_reg <= ATT_THR / ATT_SCALE), 1)) { mn = m_reg; alpha = 1.f; }
;     else { mn = fmaxf(m_reg, pmax); alpha = __builtin_amdgcn_exp2f((m_reg - mn) * C); m_reg = mn; }
;     const float mnC = -mn * C; float ps;
;     if (__any(alpha < 1.f)) { if (hi == 0) al_l[r32] = alpha; asm volatile("s_waitcnt lgkmcnt(0)" ::: "memory");
.LBB0_676:
.LBB0_677:
	s_mul_i32 s4, s4, 0xc000
	s_waitcnt lgkmcnt(0)
	v_add_u32_e32 v0, s4, v221
	v_add_u32_e32 v248, v0, v233
	v_add_u32_e32 v249, v0, v234
	v_add_u32_e32 v250, v0, v235
	v_add_u32_e32 v0, v0, v236
	ds_read_b128 v[130:133], v248 offset:0
	ds_read_b128 v[134:137], v249 offset:0
	ds_read_b128 v[138:141], v250 offset:0
	ds_read_b128 v[142:145], v0 offset:0
	ds_read_b128 v[194:197], v248 offset:0x80
	ds_read_b128 v[198:201], v249 offset:0x80
	ds_read_b128 v[202:205], v250 offset:0x80
	ds_read_b128 v[206:209], v0 offset:0x80
	s_cmpk_eq_i32 s34, 0xff
	s_cbranch_scc1 .Lnodma_b
	s_cmp_eq_u32 s4, 0
	s_cselect_b32 m0, s35, s0
	s_cselect_b32 s5, s89, 0x2000
	s_cselect_b32 s6, s44, s1
	s_cselect_b32 s7, s45, s24
	s_cselect_b32 s8, s48, s25
	s_cselect_b32 s9, s49, s28
	global_load_lds_dwordx4 v224, s[98:99]
	s_add_i32 m0, s0, s5
	s_nop 0
	global_load_lds_dwordx4 v226, s[98:99]
	s_mov_b32 m0, s6
	s_add_u32 s98, s98, 0x100000
	s_addc_u32 s99, s99, 0
	global_load_lds_dwordx4 v222, s[100:101]
	s_mov_b32 m0, s7
	s_add_u32 s100, s100, 0x2000
	s_addc_u32 s101, s101, 0
	global_load_lds_dwordx4 v222, s[100:101]
	s_mov_b32 m0, s8
	s_add_u32 s100, s100, 0x2000
	s_addc_u32 s101, s101, 0
	global_load_lds_dwordx4 v222, s[100:101]
	s_mov_b32 m0, s9
	s_add_u32 s100, s100, 0x2000
	s_addc_u32 s101, s101, 0
	global_load_lds_dwordx4 v222, s[100:101]
	s_add_u32 s100, s100, 0x2000
	s_addc_u32 s101, s101, 0
.Lnodma_b:
	s_waitcnt lgkmcnt(7)
	s_nop 0
	v_mfma_f32_32x32x16_bf16 v[146:161], v[130:133], v[162:165], 0
	ds_read_b128 v[130:133], v248 offset:0x2000
	s_waitcnt lgkmcnt(7)
	s_nop 0
	v_mfma_f32_32x32x16_bf16 v[146:161], v[134:137], v[166:169], v[146:161]
	ds_read_b128 v[212:215], v249 offset:0x2000
	s_waitcnt lgkmcnt(7)
	s_nop 0
	v_mfma_f32_32x32x16_bf16 v[146:161], v[138:141], v[170:173], v[146:161]
	ds_read_b128 v[240:243], v250 offset:0x2000
	s_waitcnt lgkmcnt(7)
	s_nop 0
	v_mfma_f32_32x32x16_bf16 v[146:161], v[142:145], v[174:177], v[146:161]
	ds_read_b128 v[244:247], v0 offset:0x2000
	s_waitcnt lgkmcnt(7)
	s_nop 0
	v_mfma_f32_32x32x16_bf16 v[146:161], v[194:197], v[178:181], v[146:161]
	ds_read_b128 v[194:197], v248 offset:0x2080
	s_waitcnt lgkmcnt(7)
	s_nop 0
	v_mfma_f32_32x32x16_bf16 v[146:161], v[198:201], v[182:185], v[146:161]
	ds_read_b128 v[198:201], v249 offset:0x2080
	s_waitcnt lgkmcnt(7)
	s_nop 0
	v_mfma_f32_32x32x16_bf16 v[146:161], v[202:205], v[186:189], v[146:161]
	ds_read_b128 v[202:205], v250 offset:0x2080
	s_waitcnt lgkmcnt(7)
	s_nop 0
	v_mfma_f32_32x32x16_bf16 v[146:161], v[206:209], v[190:193], v[146:161]
	ds_read_b128 v[206:209], v0 offset:0x2080
	s_waitcnt lgkmcnt(7)
	s_nop 11
	v_max_f32_e32 v0, v147, v147
	v_max_f32_e32 v248, v146, v146
	v_mfma_f32_32x32x16_bf16 v[130:145], v[130:133], v[162:165], 0
	v_max_f32_e32 v0, v248, v0
	s_waitcnt lgkmcnt(6)
	s_nop 0
	v_mfma_f32_32x32x16_bf16 v[130:145], v[212:215], v[166:169], v[130:145]
	v_max3_f32 v0, v0, v148, v149
	s_waitcnt lgkmcnt(5)
	s_nop 0
	v_mfma_f32_32x32x16_bf16 v[130:145], v[240:243], v[170:173], v[130:145]
	v_max3_f32 v0, v0, v150, v151
	s_waitcnt lgkmcnt(4)
	s_nop 0
	v_mfma_f32_32x32x16_bf16 v[130:145], v[244:247], v[174:177], v[130:145]
	v_max3_f32 v0, v0, v152, v153
	s_waitcnt lgkmcnt(3)
	s_nop 0
	v_mfma_f32_32x32x16_bf16 v[130:145], v[194:197], v[178:181], v[130:145]
	v_max3_f32 v0, v0, v154, v155
	s_waitcnt lgkmcnt(2)
	s_nop 0
	v_mfma_f32_32x32x16_bf16 v[130:145], v[198:201], v[182:185], v[130:145]
	v_max3_f32 v0, v0, v156, v157
	s_waitcnt lgkmcnt(1)
	s_nop 0
	v_mfma_f32_32x32x16_bf16 v[130:145], v[202:205], v[186:189], v[130:145]
	v_max3_f32 v0, v0, v158, v159
	s_waitcnt lgkmcnt(0)
	s_nop 0
	v_mfma_f32_32x32x16_bf16 v[130:145], v[206:209], v[190:193], v[130:145]
	v_max3_f32 v0, v0, v160, v161
	s_nop 10
	v_max3_f32 v0, v0, v130, v131
	v_max3_f32 v0, v0, v132, v133
	v_max3_f32 v0, v0, v134, v135
	v_max3_f32 v0, v0, v136, v137
	v_max3_f32 v0, v0, v138, v139
	v_max3_f32 v0, v0, v140, v141
	v_max3_f32 v0, v0, v142, v143
	v_max3_f32 v0, v0, v144, v145
	v_mov_b32_e32 v194, v0
	s_nop 1
	v_permlane32_swap_b32_e32 v0, v194
	v_max_f32_e32 v194, v194, v194
	v_max_f32_e32 v0, v0, v0
	v_max_f32_e32 v194, v0, v194
	v_sub_f32_e32 v0, v194, v238
	v_cmp_ge_f32_e32 vcc, s93, v0
	s_cmp_eq_u64 vcc, exec
	v_mov_b32_e32 v0, 1.0
	s_cbranch_scc0 .LBB0_684
	v_cmp_gt_f32_e32 vcc, 1.0, v0
	s_cbranch_vccz .LBB0_682
